# S5-phase weight transposes read the once-read f32 weights with nt loads
# speedup vs baseline: 1.0047x; 1.0047x over previous
.LBB0_295:
	s_cmpk_gt_i32 s5, 0x1fff
	s_mov_b64 s[10:11], -1
	s_cbranch_scc0 .LBB0_317
	s_cmpk_gt_u32 s5, 0x3fff
	s_cbranch_scc0 .LBB0_310
	s_cmpk_gt_u32 s5, 0x43ff
	s_cbranch_scc0 .LBB0_307
	s_cmpk_gt_u32 s5, 0x4fff
	s_cbranch_scc0 .LBB0_304
	s_cmpk_gt_u32 s5, 0x5bff
	s_cbranch_scc0 .LBB0_301
	s_add_i32 s10, s5, 0xffffa400
	s_lshr_b32 s66, s10, 9
	s_lshl_b64 s[10:11], s[66:67], 22
	s_add_u32 s12, s50, s10
	s_addc_u32 s13, s51, s11
	s_lshl_b64 s[10:11], s[66:67], 21
	v_readlane_b32 s17, v252, 63
	s_add_u32 s17, s17, s10
	v_readlane_b32 s10, v253, 0
	s_addc_u32 s11, s10, s11
	s_lshl_b32 s10, s5, 1
	s_and_b32 s20, s10, 0x3c0
	s_lshl_b32 s10, s5, 5
	s_and_b32 s10, s10, 0x3e0
	s_lshl_b32 s21, s10, 2
	v_add_u32_e32 v30, s20, v10
	s_add_u32 s12, s12, s21
	s_addc_u32 s13, s13, 0
	v_ashrrev_i32_e32 v31, 31, v30
	v_lshl_add_u64 v[32:33], s[12:13], 0, v[152:153]
	v_lshlrev_b64 v[30:31], 12, v[30:31]
	v_lshl_add_u64 v[58:59], v[32:33], 0, v[30:31]
	s_mov_b32 s12, 0x8000
	v_add_co_u32_e32 v34, vcc, s12, v58
	s_mov_b32 s12, 0x10000
	s_nop 0
	v_addc_co_u32_e32 v35, vcc, 0, v59, vcc
	v_add_co_u32_e32 v38, vcc, s12, v58
	s_mov_b32 s12, 0x18000
	s_nop 0
	v_addc_co_u32_e32 v39, vcc, 0, v59, vcc
	v_add_co_u32_e32 v42, vcc, s12, v58
	s_mov_b32 s12, 0x28000
	s_nop 0
	v_addc_co_u32_e32 v43, vcc, 0, v59, vcc
	v_add_co_u32_e32 v46, vcc, s76, v58
	global_load_dwordx4 v[30:33], v[58:59], off nt
	s_nop 0
	global_load_dwordx4 v[34:37], v[34:35], off nt
	v_addc_co_u32_e32 v47, vcc, 0, v59, vcc
	v_add_co_u32_e32 v50, vcc, s12, v58
	global_load_dwordx4 v[38:41], v[38:39], off nt
	s_nop 0
	global_load_dwordx4 v[42:45], v[42:43], off nt
	v_addc_co_u32_e32 v51, vcc, 0, v59, vcc
	global_load_dwordx4 v[46:49], v[46:47], off nt
	s_nop 0
	global_load_dwordx4 v[50:53], v[50:51], off nt
	s_mov_b32 s12, 0x30000
	v_add_co_u32_e32 v54, vcc, s12, v58
	s_mov_b32 s12, 0x38000
	s_nop 0
	v_addc_co_u32_e32 v55, vcc, 0, v59, vcc
	global_load_dwordx4 v[54:57], v[54:55], off nt
	v_add_co_u32_e32 v58, vcc, s12, v58
	s_lshl_b32 s12, s20, 1
	s_nop 0
	v_addc_co_u32_e32 v59, vcc, 0, v59, vcc
	global_load_dwordx4 v[58:61], v[58:59], off nt
	v_add_u32_e32 v62, s10, v10
	s_add_u32 s12, s17, s12
	v_mov_b32_e32 v9, v153
	v_ashrrev_i32_e32 v63, 31, v62
	s_addc_u32 s13, s11, 0
	v_lshlrev_b64 v[62:63], 11, v[62:63]
	v_lshl_add_u64 v[66:67], s[12:13], 0, v[8:9]
	v_add_u32_e32 v64, s10, v11
	v_lshl_add_u64 v[62:63], v[66:67], 0, v[62:63]
	v_ashrrev_i32_e32 v65, 31, v64
	v_lshlrev_b64 v[64:65], 11, v[64:65]
	s_waitcnt vmcnt(7)
	ds_write2_b32 v15, v30, v31 offset1:1
	ds_write2_b32 v15, v32, v33 offset0:2 offset1:3
	s_waitcnt vmcnt(6)
	ds_write2_b32 v16, v34, v35 offset1:1
	ds_write2_b32 v17, v36, v37 offset1:1
	s_waitcnt vmcnt(5)
	ds_write2_b32 v18, v38, v39 offset1:1
	ds_write2_b32 v19, v40, v41 offset1:1
	s_waitcnt vmcnt(4)
	ds_write2_b32 v20, v42, v43 offset1:1
	ds_write2_b32 v21, v44, v45 offset1:1
	s_waitcnt vmcnt(3)
	ds_write2_b32 v22, v46, v47 offset1:1
	ds_write2_b32 v23, v48, v49 offset1:1
	s_waitcnt vmcnt(2)
	ds_write2_b32 v24, v50, v51 offset1:1
	ds_write2_b32 v25, v52, v53 offset1:1
	s_waitcnt vmcnt(1)
	ds_write2_b32 v26, v54, v55 offset1:1
	ds_write2_b32 v27, v56, v57 offset1:1
	s_waitcnt vmcnt(0)
	ds_write2_b32 v28, v58, v59 offset1:1
	ds_write2_b32 v29, v60, v61 offset1:1
	s_waitcnt lgkmcnt(0)
	ds_read2_b32 v[34:35], v14 offset0:33 offset1:41
	ds_read2_b32 v[36:37], v14 offset1:8
	ds_read2_b32 v[38:39], v14 offset0:66 offset1:74
	ds_read2_b32 v[40:41], v14 offset0:99 offset1:107
	ds_read2_b32 v[42:43], v14 offset0:132 offset1:140
	ds_read2_b32 v[44:45], v14 offset0:165 offset1:173
	ds_read2_b32 v[46:47], v14 offset0:198 offset1:206
	ds_read2_b32 v[48:49], v14 offset0:231 offset1:239
	s_waitcnt lgkmcnt(6)
	v_cvt_pk_bf16_f32 v30, v36, v34
	s_waitcnt lgkmcnt(4)
	v_cvt_pk_bf16_f32 v31, v38, v40
	s_waitcnt lgkmcnt(2)
	v_cvt_pk_bf16_f32 v32, v42, v44
	v_cvt_pk_bf16_f32 v34, v37, v35
	s_waitcnt lgkmcnt(0)
	v_cvt_pk_bf16_f32 v33, v46, v48
	global_store_dwordx4 v[62:63], v[30:33], off
	v_cvt_pk_bf16_f32 v35, v39, v41
	v_cvt_pk_bf16_f32 v36, v43, v45
	v_cvt_pk_bf16_f32 v37, v47, v49
	ds_read2_b32 v[38:39], v14 offset0:49 offset1:57
	ds_read2_b32 v[40:41], v14 offset0:16 offset1:24
	ds_read2_b32 v[42:43], v14 offset0:82 offset1:90
	ds_read2_b32 v[44:45], v14 offset0:115 offset1:123
	ds_read2_b32 v[46:47], v14 offset0:148 offset1:156
	ds_read2_b32 v[48:49], v14 offset0:181 offset1:189
	ds_read2_b32 v[52:53], v14 offset0:214 offset1:222
	ds_read2_b32 v[54:55], v14 offset0:247 offset1:255
	v_lshl_add_u64 v[50:51], v[66:67], 0, v[64:65]
	global_store_dwordx4 v[50:51], v[34:37], off
	s_waitcnt lgkmcnt(6)
	v_cvt_pk_bf16_f32 v30, v40, v38
	s_waitcnt lgkmcnt(4)
	v_cvt_pk_bf16_f32 v31, v42, v44
	v_add_u32_e32 v34, s10, v12
	v_ashrrev_i32_e32 v35, 31, v34
	v_lshlrev_b64 v[34:35], 11, v[34:35]
	s_waitcnt lgkmcnt(2)
	v_cvt_pk_bf16_f32 v32, v46, v48
	s_waitcnt lgkmcnt(0)
	v_cvt_pk_bf16_f32 v33, v52, v54
	v_lshl_add_u64 v[34:35], v[66:67], 0, v[34:35]
	global_store_dwordx4 v[34:35], v[30:33], off
	v_add_u32_e32 v34, s10, v13
	v_ashrrev_i32_e32 v35, 31, v34
	v_lshlrev_b64 v[34:35], 11, v[34:35]
	v_cvt_pk_bf16_f32 v30, v41, v39
	v_cvt_pk_bf16_f32 v31, v43, v45
	v_cvt_pk_bf16_f32 v32, v47, v49
	v_cvt_pk_bf16_f32 v33, v53, v55
	v_lshl_add_u64 v[34:35], v[66:67], 0, v[34:35]
	global_store_dwordx4 v[34:35], v[30:33], off
	s_waitcnt lgkmcnt(0)
	s_mov_b64 s[10:11], 0
.LBB0_301:
	s_andn2_b64 vcc, exec, s[10:11]
	s_cbranch_vccnz .LBB0_303
	s_add_i32 s10, s5, 0xffffb000
	s_cmpk_gt_u32 s10, 0x5ff
	s_cselect_b32 s11, 0xc00000, 0
	s_cselect_b32 s12, 0x600000, 0
	s_add_u32 s13, s48, s11
	s_addc_u32 s17, s49, 0
	v_readlane_b32 s11, v252, 61
	s_add_u32 s22, s11, s12
	v_readlane_b32 s11, v252, 62
	s_addc_u32 s23, s11, 0
	s_add_i32 s11, s5, 0xffffaa00
	s_cmpk_lt_u32 s10, 0x600
	s_cselect_b32 s10, s10, s11
	s_sext_i32_i16 s11, s10
	s_mulk_i32 s11, 0x2aab
	s_lshr_b32 s12, s11, 31
	s_ashr_i32 s11, s11, 20
	s_add_i32 s11, s11, s12
	s_sext_i32_i16 s12, s11
	s_mulk_i32 s11, 0x60
	s_sub_i32 s10, s10, s11
	s_sext_i32_i16 s10, s10
	s_lshl_b32 s10, s10, 5
	s_ashr_i32 s11, s10, 31
	s_lshl_b32 s12, s12, 6
	s_lshl_b64 s[20:21], s[10:11], 2
	s_add_u32 s20, s13, s20
	v_add_u32_e32 v9, s12, v10
	s_addc_u32 s21, s17, s21
	v_lshl_add_u64 v[58:59], s[20:21], 0, v[152:153]
	s_movk_i32 s11, 0x3000
	v_add_u32_e32 v32, 8, v9
	v_add_u32_e32 v38, 16, v9
	v_add_u32_e32 v40, 24, v9
	v_add_u32_e32 v46, 32, v9
	v_add_u32_e32 v48, 40, v9
	v_mad_i64_i32 v[30:31], s[20:21], v9, s11, v[58:59]
	v_mad_i64_i32 v[34:35], s[20:21], v32, s11, v[58:59]
	v_mad_i64_i32 v[38:39], s[20:21], v38, s11, v[58:59]
	v_mad_i64_i32 v[42:43], s[20:21], v40, s11, v[58:59]
	v_mad_i64_i32 v[46:47], s[20:21], v46, s11, v[58:59]
	v_mad_i64_i32 v[50:51], s[20:21], v48, s11, v[58:59]
	global_load_dwordx4 v[30:33], v[30:31], off nt
	s_nop 0
	global_load_dwordx4 v[34:37], v[34:35], off nt
	s_nop 0
	global_load_dwordx4 v[38:41], v[38:39], off nt
	s_nop 0
	global_load_dwordx4 v[42:45], v[42:43], off nt
	s_nop 0
	global_load_dwordx4 v[46:49], v[46:47], off nt
	s_nop 0
	global_load_dwordx4 v[50:53], v[50:51], off nt
	v_add_u32_e32 v54, 48, v9
	v_mad_i64_i32 v[54:55], s[20:21], v54, s11, v[58:59]
	global_load_dwordx4 v[54:57], v[54:55], off nt
	v_add_u32_e32 v9, 56, v9
	v_mad_i64_i32 v[58:59], s[20:21], v9, s11, v[58:59]
	global_load_dwordx4 v[58:61], v[58:59], off nt
	s_ashr_i32 s13, s12, 31
	s_lshl_b64 s[12:13], s[12:13], 1
	v_add_u32_e32 v62, s10, v10
	s_add_u32 s12, s22, s12
	v_mov_b32_e32 v9, v153
	v_ashrrev_i32_e32 v63, 31, v62
	s_addc_u32 s13, s23, s13
	v_lshlrev_b64 v[62:63], 11, v[62:63]
	v_lshl_add_u64 v[66:67], s[12:13], 0, v[8:9]
	v_add_u32_e32 v64, s10, v11
	v_lshl_add_u64 v[62:63], v[66:67], 0, v[62:63]
	v_ashrrev_i32_e32 v65, 31, v64
	v_lshlrev_b64 v[64:65], 11, v[64:65]
	v_lshl_add_u64 v[64:65], v[66:67], 0, v[64:65]
	s_waitcnt vmcnt(7)
	ds_write2_b32 v15, v30, v31 offset1:1
	ds_write2_b32 v15, v32, v33 offset0:2 offset1:3
	s_waitcnt vmcnt(6)
	ds_write2_b32 v16, v34, v35 offset1:1
	ds_write2_b32 v17, v36, v37 offset1:1
	s_waitcnt vmcnt(5)
	ds_write2_b32 v18, v38, v39 offset1:1
	ds_write2_b32 v19, v40, v41 offset1:1
	s_waitcnt vmcnt(4)
	ds_write2_b32 v20, v42, v43 offset1:1
	ds_write2_b32 v21, v44, v45 offset1:1
	s_waitcnt vmcnt(3)
	ds_write2_b32 v22, v46, v47 offset1:1
	ds_write2_b32 v23, v48, v49 offset1:1
	s_waitcnt vmcnt(2)
	ds_write2_b32 v24, v50, v51 offset1:1
	ds_write2_b32 v25, v52, v53 offset1:1
	s_waitcnt vmcnt(1)
	ds_write2_b32 v26, v54, v55 offset1:1
	ds_write2_b32 v27, v56, v57 offset1:1
	s_waitcnt vmcnt(0)
	ds_write2_b32 v28, v58, v59 offset1:1
	ds_write2_b32 v29, v60, v61 offset1:1
	s_waitcnt lgkmcnt(0)
	ds_read2_b32 v[34:35], v14 offset0:33 offset1:41
	ds_read2_b32 v[36:37], v14 offset1:8
	ds_read2_b32 v[38:39], v14 offset0:66 offset1:74
	ds_read2_b32 v[40:41], v14 offset0:99 offset1:107
	ds_read2_b32 v[42:43], v14 offset0:132 offset1:140
	ds_read2_b32 v[44:45], v14 offset0:165 offset1:173
	ds_read2_b32 v[46:47], v14 offset0:198 offset1:206
	ds_read2_b32 v[48:49], v14 offset0:231 offset1:239
	ds_read2_b32 v[50:51], v14 offset0:49 offset1:57
	ds_read2_b32 v[52:53], v14 offset0:16 offset1:24
	ds_read2_b32 v[54:55], v14 offset0:82 offset1:90
	ds_read2_b32 v[56:57], v14 offset0:115 offset1:123
	ds_read2_b32 v[58:59], v14 offset0:148 offset1:156
	s_waitcnt lgkmcnt(11)
	v_cvt_pk_bf16_f32 v30, v36, v34
	s_waitcnt lgkmcnt(9)
	v_cvt_pk_bf16_f32 v31, v38, v40
	s_waitcnt lgkmcnt(7)
	v_cvt_pk_bf16_f32 v32, v42, v44
	s_waitcnt lgkmcnt(5)
	v_cvt_pk_bf16_f32 v33, v46, v48
	global_store_dwordx4 v[62:63], v[30:33], off
	v_cvt_pk_bf16_f32 v34, v37, v35
	v_cvt_pk_bf16_f32 v35, v39, v41
	v_cvt_pk_bf16_f32 v36, v43, v45
	ds_read2_b32 v[38:39], v14 offset0:181 offset1:189
	ds_read2_b32 v[40:41], v14 offset0:214 offset1:222
	ds_read2_b32 v[42:43], v14 offset0:247 offset1:255
	v_cvt_pk_bf16_f32 v37, v47, v49
	global_store_dwordx4 v[64:65], v[34:37], off
	s_waitcnt lgkmcnt(6)
	v_cvt_pk_bf16_f32 v30, v52, v50
	s_waitcnt lgkmcnt(4)
	v_cvt_pk_bf16_f32 v31, v54, v56
	v_add_u32_e32 v34, s10, v12
	v_ashrrev_i32_e32 v35, 31, v34
	v_lshlrev_b64 v[34:35], 11, v[34:35]
	s_waitcnt lgkmcnt(2)
	v_cvt_pk_bf16_f32 v32, v58, v38
	s_waitcnt lgkmcnt(0)
	v_cvt_pk_bf16_f32 v33, v40, v42
	v_lshl_add_u64 v[34:35], v[66:67], 0, v[34:35]
	global_store_dwordx4 v[34:35], v[30:33], off
	v_add_u32_e32 v34, s10, v13
	v_ashrrev_i32_e32 v35, 31, v34
	v_lshlrev_b64 v[34:35], 11, v[34:35]
	v_cvt_pk_bf16_f32 v30, v53, v51
	v_cvt_pk_bf16_f32 v31, v55, v57
	v_cvt_pk_bf16_f32 v32, v59, v39
	v_cvt_pk_bf16_f32 v33, v41, v43
	v_lshl_add_u64 v[34:35], v[66:67], 0, v[34:35]
	global_store_dwordx4 v[34:35], v[30:33], off
	s_waitcnt lgkmcnt(0)

.LBB0_304:
	s_andn2_b64 vcc, exec, s[10:11]
	s_cbranch_vccnz .LBB0_306
	s_add_i32 s10, s5, 0xbc00
	s_and_b32 s11, s10, 0xffff
	s_mul_i32 s11, s11, 0xaaab
	s_lshr_b32 s12, s11, 23
	s_mul_i32 s11, s12, 0xc0
	s_sub_i32 s10, s10, s11
	s_lshl_b32 s10, s10, 5
	s_and_b32 s13, s10, 0xffe0
	v_lshl_add_u32 v9, s12, 6, v10
	s_lshl_b32 s66, s13, 2
	v_lshl_add_u64 v[58:59], v[0:1], 0, s[66:67]
	s_movk_i32 s14, 0x6000
	v_add_u32_e32 v32, 8, v9
	v_add_u32_e32 v38, 16, v9
	v_add_u32_e32 v40, 24, v9
	v_add_u32_e32 v46, 32, v9
	v_add_u32_e32 v48, 40, v9
	v_mad_i64_i32 v[30:31], s[10:11], v9, s14, v[58:59]
	v_mad_i64_i32 v[34:35], s[10:11], v32, s14, v[58:59]
	v_mad_i64_i32 v[38:39], s[10:11], v38, s14, v[58:59]
	v_mad_i64_i32 v[42:43], s[10:11], v40, s14, v[58:59]
	v_mad_i64_i32 v[46:47], s[10:11], v46, s14, v[58:59]
	v_mad_i64_i32 v[50:51], s[10:11], v48, s14, v[58:59]
	global_load_dwordx4 v[30:33], v[30:31], off nt
	s_nop 0
	global_load_dwordx4 v[34:37], v[34:35], off nt
	s_nop 0
	global_load_dwordx4 v[38:41], v[38:39], off nt
	s_nop 0
	global_load_dwordx4 v[42:45], v[42:43], off nt
	s_nop 0
	global_load_dwordx4 v[46:49], v[46:47], off nt
	s_nop 0
	global_load_dwordx4 v[50:53], v[50:51], off nt
	v_add_u32_e32 v54, 48, v9
	v_mad_i64_i32 v[54:55], s[10:11], v54, s14, v[58:59]
	global_load_dwordx4 v[54:57], v[54:55], off nt
	v_add_u32_e32 v9, 56, v9
	v_mad_i64_i32 v[58:59], s[10:11], v9, s14, v[58:59]
	global_load_dwordx4 v[58:61], v[58:59], off nt
	v_add_u32_e32 v62, s13, v10
	v_add_u32_e32 v64, s13, v11
	s_lshl_b32 s66, s12, 7
	v_ashrrev_i32_e32 v63, 31, v62
	v_ashrrev_i32_e32 v65, 31, v64
	v_lshl_add_u64 v[68:69], v[2:3], 0, s[66:67]
	v_lshlrev_b64 v[62:63], 11, v[62:63]
	v_add_u32_e32 v66, s13, v12
	v_lshlrev_b64 v[64:65], 11, v[64:65]
	v_lshl_add_u64 v[62:63], v[68:69], 0, v[62:63]
	v_lshl_add_u64 v[64:65], v[68:69], 0, v[64:65]
	v_ashrrev_i32_e32 v67, 31, v66
	s_waitcnt vmcnt(7)
	ds_write2_b32 v15, v30, v31 offset1:1
	ds_write2_b32 v15, v32, v33 offset0:2 offset1:3
	s_waitcnt vmcnt(6)
	ds_write2_b32 v16, v34, v35 offset1:1
	ds_write2_b32 v17, v36, v37 offset1:1
	s_waitcnt vmcnt(5)
	ds_write2_b32 v18, v38, v39 offset1:1
	ds_write2_b32 v19, v40, v41 offset1:1
	s_waitcnt vmcnt(4)
	ds_write2_b32 v20, v42, v43 offset1:1
	ds_write2_b32 v21, v44, v45 offset1:1
	s_waitcnt vmcnt(3)
	ds_write2_b32 v22, v46, v47 offset1:1
	ds_write2_b32 v23, v48, v49 offset1:1
	s_waitcnt vmcnt(2)
	ds_write2_b32 v24, v50, v51 offset1:1
	ds_write2_b32 v25, v52, v53 offset1:1
	s_waitcnt vmcnt(1)
	ds_write2_b32 v26, v54, v55 offset1:1
	ds_write2_b32 v27, v56, v57 offset1:1
	s_waitcnt vmcnt(0)
	ds_write2_b32 v28, v58, v59 offset1:1
	ds_write2_b32 v29, v60, v61 offset1:1
	s_waitcnt lgkmcnt(0)
	ds_read2_b32 v[34:35], v14 offset0:33 offset1:41
	ds_read2_b32 v[36:37], v14 offset1:8
	ds_read2_b32 v[38:39], v14 offset0:66 offset1:74
	ds_read2_b32 v[40:41], v14 offset0:99 offset1:107
	ds_read2_b32 v[42:43], v14 offset0:132 offset1:140
	ds_read2_b32 v[44:45], v14 offset0:165 offset1:173
	ds_read2_b32 v[46:47], v14 offset0:198 offset1:206
	ds_read2_b32 v[48:49], v14 offset0:231 offset1:239
	ds_read2_b32 v[50:51], v14 offset0:49 offset1:57
	ds_read2_b32 v[52:53], v14 offset0:16 offset1:24
	ds_read2_b32 v[54:55], v14 offset0:82 offset1:90
	ds_read2_b32 v[56:57], v14 offset0:115 offset1:123
	ds_read2_b32 v[58:59], v14 offset0:148 offset1:156
	ds_read2_b32 v[60:61], v14 offset0:181 offset1:189
	ds_read2_b32 v[70:71], v14 offset0:214 offset1:222
	ds_read2_b32 v[72:73], v14 offset0:247 offset1:255
	s_waitcnt lgkmcnt(14)
	v_cvt_pk_bf16_f32 v30, v36, v34
	s_waitcnt lgkmcnt(12)
	v_cvt_pk_bf16_f32 v31, v38, v40
	s_waitcnt lgkmcnt(10)
	v_cvt_pk_bf16_f32 v32, v42, v44
	s_waitcnt lgkmcnt(8)
	v_cvt_pk_bf16_f32 v33, v46, v48
	v_cvt_pk_bf16_f32 v34, v37, v35
	v_cvt_pk_bf16_f32 v35, v39, v41
	v_cvt_pk_bf16_f32 v36, v43, v45
	v_cvt_pk_bf16_f32 v37, v47, v49
	global_store_dwordx4 v[62:63], v[30:33], off
	global_store_dwordx4 v[64:65], v[34:37], off
	s_waitcnt lgkmcnt(6)
	v_cvt_pk_bf16_f32 v38, v52, v50
	v_lshlrev_b64 v[30:31], 11, v[66:67]
	v_add_u32_e32 v34, s13, v13
	v_ashrrev_i32_e32 v35, 31, v34
	s_waitcnt lgkmcnt(4)
	v_cvt_pk_bf16_f32 v39, v54, v56
	s_waitcnt lgkmcnt(2)
	v_cvt_pk_bf16_f32 v40, v58, v60
	s_waitcnt lgkmcnt(0)
	v_cvt_pk_bf16_f32 v41, v70, v72
	v_lshl_add_u64 v[30:31], v[68:69], 0, v[30:31]
	v_lshlrev_b64 v[34:35], 11, v[34:35]
	global_store_dwordx4 v[30:31], v[38:41], off
	v_cvt_pk_bf16_f32 v30, v53, v51
	v_cvt_pk_bf16_f32 v31, v55, v57
	v_cvt_pk_bf16_f32 v32, v59, v61
	v_cvt_pk_bf16_f32 v33, v71, v73
	v_lshl_add_u64 v[34:35], v[68:69], 0, v[34:35]
	global_store_dwordx4 v[34:35], v[30:33], off
	s_waitcnt lgkmcnt(0)

.LBB0_307:
	s_andn2_b64 vcc, exec, s[10:11]
	s_cbranch_vccnz .LBB0_309
	s_add_i32 s10, s5, 0xc000
	s_and_b32 s10, s10, 0xffc0
	v_add_u32_e32 v30, s10, v10
	s_lshl_b32 s11, s5, 7
	s_and_b32 s66, s11, 0x1f80
	v_ashrrev_i32_e32 v31, 31, v30
	v_lshl_add_u64 v[32:33], v[4:5], 0, s[66:67]
	v_lshlrev_b64 v[30:31], 13, v[30:31]
	v_lshl_add_u64 v[58:59], v[32:33], 0, v[30:31]
	v_add_co_u32_e32 v34, vcc, 0x10000, v58
	s_lshl_b32 s12, s5, 6
	s_nop 0
	v_addc_co_u32_e32 v35, vcc, 0, v59, vcc
	v_add_co_u32_e32 v38, vcc, 0x20000, v58
	global_load_dwordx4 v[30:33], v[58:59], off nt
	s_nop 0
	global_load_dwordx4 v[34:37], v[34:35], off nt
	v_addc_co_u32_e32 v39, vcc, 0, v59, vcc
	v_add_co_u32_e32 v42, vcc, 0x30000, v58
	s_lshl_b32 s13, s5, 2
	s_nop 0
	v_addc_co_u32_e32 v43, vcc, 0, v59, vcc
	v_add_co_u32_e32 v46, vcc, 0x40000, v58
	global_load_dwordx4 v[38:41], v[38:39], off nt
	s_nop 0
	global_load_dwordx4 v[42:45], v[42:43], off nt
	v_addc_co_u32_e32 v47, vcc, 0, v59, vcc
	v_add_co_u32_e32 v50, vcc, 0x50000, v58
	s_lshl_b32 s11, s5, 5
	s_nop 0
	v_addc_co_u32_e32 v51, vcc, 0, v59, vcc
	global_load_dwordx4 v[46:49], v[46:47], off nt
	s_nop 0
	global_load_dwordx4 v[50:53], v[50:51], off nt
	v_add_co_u32_e32 v54, vcc, 0x60000, v58
	s_and_b32 s12, s12, 0x700
	s_nop 0
	v_addc_co_u32_e32 v55, vcc, 0, v59, vcc
	global_load_dwordx4 v[54:57], v[54:55], off nt
	v_add_co_u32_e32 v58, vcc, 0x70000, v58
	s_and_b32 s13, s13, 0x80
	s_nop 0
	v_addc_co_u32_e32 v59, vcc, 0, v59, vcc
	global_load_dwordx4 v[58:61], v[58:59], off nt
	s_and_b32 s11, s11, 0x60
	s_or_b32 s12, s12, s13
	s_lshl_b32 s66, s10, 1
	s_or_b32 s10, s12, s11
	v_add_u32_e32 v64, s10, v10
	v_ashrrev_i32_e32 v65, 31, v64
	v_lshl_add_u64 v[62:63], v[6:7], 0, s[66:67]
	v_lshlrev_b64 v[64:65], 11, v[64:65]
	v_add_u32_e32 v66, s10, v11
	v_ashrrev_i32_e32 v67, 31, v66
	v_lshlrev_b64 v[66:67], 11, v[66:67]
	s_waitcnt vmcnt(7)
	ds_write2_b32 v15, v30, v31 offset1:1
	ds_write2_b32 v15, v32, v33 offset0:2 offset1:3
	s_waitcnt vmcnt(6)
	ds_write2_b32 v16, v34, v35 offset1:1
	ds_write2_b32 v17, v36, v37 offset1:1
	s_waitcnt vmcnt(5)
	ds_write2_b32 v18, v38, v39 offset1:1
	ds_write2_b32 v19, v40, v41 offset1:1
	s_waitcnt vmcnt(4)
	ds_write2_b32 v20, v42, v43 offset1:1
	ds_write2_b32 v21, v44, v45 offset1:1
	s_waitcnt vmcnt(3)
	ds_write2_b32 v22, v46, v47 offset1:1
	ds_write2_b32 v23, v48, v49 offset1:1
	s_waitcnt vmcnt(2)
	ds_write2_b32 v24, v50, v51 offset1:1
	ds_write2_b32 v25, v52, v53 offset1:1
	s_waitcnt vmcnt(1)
	ds_write2_b32 v26, v54, v55 offset1:1
	ds_write2_b32 v27, v56, v57 offset1:1
	s_waitcnt vmcnt(0)
	ds_write2_b32 v28, v58, v59 offset1:1
	ds_write2_b32 v29, v60, v61 offset1:1
	s_waitcnt lgkmcnt(0)
	ds_read2_b32 v[34:35], v14 offset0:33 offset1:41
	ds_read2_b32 v[36:37], v14 offset1:8
	ds_read2_b32 v[38:39], v14 offset0:66 offset1:74
	ds_read2_b32 v[40:41], v14 offset0:99 offset1:107
	ds_read2_b32 v[42:43], v14 offset0:132 offset1:140
	ds_read2_b32 v[44:45], v14 offset0:165 offset1:173
	ds_read2_b32 v[46:47], v14 offset0:198 offset1:206
	ds_read2_b32 v[48:49], v14 offset0:231 offset1:239
	v_lshl_add_u64 v[50:51], v[62:63], 0, v[64:65]
	s_waitcnt lgkmcnt(6)
	v_cvt_pk_bf16_f32 v30, v36, v34
	s_waitcnt lgkmcnt(4)
	v_cvt_pk_bf16_f32 v31, v38, v40
	s_waitcnt lgkmcnt(2)
	v_cvt_pk_bf16_f32 v32, v42, v44
	s_waitcnt lgkmcnt(0)
	v_cvt_pk_bf16_f32 v33, v46, v48
	global_store_dwordx4 v[50:51], v[30:33], off
	v_cvt_pk_bf16_f32 v34, v37, v35
	v_cvt_pk_bf16_f32 v35, v39, v41
	v_cvt_pk_bf16_f32 v36, v43, v45
	v_cvt_pk_bf16_f32 v37, v47, v49
	ds_read2_b32 v[38:39], v14 offset0:49 offset1:57
	ds_read2_b32 v[40:41], v14 offset0:16 offset1:24
	ds_read2_b32 v[42:43], v14 offset0:82 offset1:90
	ds_read2_b32 v[44:45], v14 offset0:115 offset1:123
	ds_read2_b32 v[46:47], v14 offset0:148 offset1:156
	ds_read2_b32 v[48:49], v14 offset0:181 offset1:189
	ds_read2_b32 v[50:51], v14 offset0:214 offset1:222
	ds_read2_b32 v[52:53], v14 offset0:247 offset1:255
	v_lshl_add_u64 v[30:31], v[62:63], 0, v[66:67]
	global_store_dwordx4 v[30:31], v[34:37], off
	s_waitcnt lgkmcnt(6)
	v_cvt_pk_bf16_f32 v30, v40, v38
	s_waitcnt lgkmcnt(4)
	v_cvt_pk_bf16_f32 v31, v42, v44
	v_add_u32_e32 v34, s10, v12
	v_ashrrev_i32_e32 v35, 31, v34
	v_lshlrev_b64 v[34:35], 11, v[34:35]
	s_waitcnt lgkmcnt(2)
	v_cvt_pk_bf16_f32 v32, v46, v48
	s_waitcnt lgkmcnt(0)
	v_cvt_pk_bf16_f32 v33, v50, v52
	v_lshl_add_u64 v[34:35], v[62:63], 0, v[34:35]
	global_store_dwordx4 v[34:35], v[30:33], off
	v_add_u32_e32 v34, s10, v13
	v_ashrrev_i32_e32 v35, 31, v34
	v_lshlrev_b64 v[34:35], 11, v[34:35]
	v_cvt_pk_bf16_f32 v30, v41, v39
	v_cvt_pk_bf16_f32 v31, v43, v45
	v_cvt_pk_bf16_f32 v32, v47, v49
	v_cvt_pk_bf16_f32 v33, v51, v53
	v_lshl_add_u64 v[34:35], v[62:63], 0, v[34:35]
	global_store_dwordx4 v[34:35], v[30:33], off
	s_waitcnt lgkmcnt(0)

.LBB0_315:
	s_lshl_b64 s[12:13], s[66:67], 24
	s_add_u32 s12, s54, s12
	s_addc_u32 s13, s55, s13
	s_add_u32 s17, s94, s10
	s_addc_u32 s11, s95, s11
	s_lshl_b32 s10, s5, 1
	s_and_b32 s20, s10, 0xfc0
	s_lshl_b32 s10, s5, 5
	s_and_b32 s10, s10, 0x3e0
	s_lshl_b32 s21, s10, 2
	v_add_u32_e32 v30, s20, v10
	s_add_u32 s12, s12, s21
	s_addc_u32 s13, s13, 0
	v_ashrrev_i32_e32 v31, 31, v30
	v_lshl_add_u64 v[32:33], s[12:13], 0, v[152:153]
	v_lshlrev_b64 v[30:31], 12, v[30:31]
	v_lshl_add_u64 v[58:59], v[32:33], 0, v[30:31]
	s_mov_b32 s12, 0x8000
	v_add_co_u32_e32 v34, vcc, s12, v58
	s_mov_b32 s12, 0x10000
	s_nop 0
	v_addc_co_u32_e32 v35, vcc, 0, v59, vcc
	v_add_co_u32_e32 v38, vcc, s12, v58
	s_mov_b32 s12, 0x18000
	s_nop 0
	v_addc_co_u32_e32 v39, vcc, 0, v59, vcc
	v_add_co_u32_e32 v42, vcc, s12, v58
	s_mov_b32 s12, 0x28000
	s_nop 0
	v_addc_co_u32_e32 v43, vcc, 0, v59, vcc
	v_add_co_u32_e32 v46, vcc, s76, v58
	global_load_dwordx4 v[30:33], v[58:59], off nt
	s_nop 0
	global_load_dwordx4 v[34:37], v[34:35], off nt
	v_addc_co_u32_e32 v47, vcc, 0, v59, vcc
	v_add_co_u32_e32 v50, vcc, s12, v58
	global_load_dwordx4 v[38:41], v[38:39], off nt
	s_nop 0
	global_load_dwordx4 v[42:45], v[42:43], off nt
	v_addc_co_u32_e32 v51, vcc, 0, v59, vcc
	global_load_dwordx4 v[46:49], v[46:47], off nt
	s_nop 0
	global_load_dwordx4 v[50:53], v[50:51], off nt
	s_mov_b32 s12, 0x30000
	v_add_co_u32_e32 v54, vcc, s12, v58
	s_mov_b32 s12, 0x38000
	s_nop 0
	v_addc_co_u32_e32 v55, vcc, 0, v59, vcc
	global_load_dwordx4 v[54:57], v[54:55], off nt
	v_add_co_u32_e32 v58, vcc, s12, v58
	s_lshl_b32 s12, s20, 1
	s_nop 0
	v_addc_co_u32_e32 v59, vcc, 0, v59, vcc
	global_load_dwordx4 v[58:61], v[58:59], off nt
	v_add_u32_e32 v62, s10, v10
	s_add_u32 s12, s17, s12
	v_mov_b32_e32 v9, v153
	v_ashrrev_i32_e32 v63, 31, v62
	s_addc_u32 s13, s11, 0
	v_lshlrev_b64 v[62:63], 13, v[62:63]
	v_lshl_add_u64 v[66:67], s[12:13], 0, v[8:9]
	v_add_u32_e32 v64, s10, v11
	v_lshl_add_u64 v[62:63], v[66:67], 0, v[62:63]
	v_ashrrev_i32_e32 v65, 31, v64
	v_lshlrev_b64 v[64:65], 13, v[64:65]
	v_lshl_add_u64 v[64:65], v[66:67], 0, v[64:65]
	s_waitcnt vmcnt(7)
	ds_write2_b32 v15, v30, v31 offset1:1
	ds_write2_b32 v15, v32, v33 offset0:2 offset1:3
	s_waitcnt vmcnt(6)
	ds_write2_b32 v16, v34, v35 offset1:1
	ds_write2_b32 v17, v36, v37 offset1:1
	s_waitcnt vmcnt(5)
	ds_write2_b32 v18, v38, v39 offset1:1
	ds_write2_b32 v19, v40, v41 offset1:1
	s_waitcnt vmcnt(4)
	ds_write2_b32 v20, v42, v43 offset1:1
	ds_write2_b32 v21, v44, v45 offset1:1
	s_waitcnt vmcnt(3)
	ds_write2_b32 v22, v46, v47 offset1:1
	ds_write2_b32 v23, v48, v49 offset1:1
	s_waitcnt vmcnt(2)
	ds_write2_b32 v24, v50, v51 offset1:1
	ds_write2_b32 v25, v52, v53 offset1:1
	s_waitcnt vmcnt(1)
	ds_write2_b32 v26, v54, v55 offset1:1
	ds_write2_b32 v27, v56, v57 offset1:1
	s_waitcnt vmcnt(0)
	ds_write2_b32 v28, v58, v59 offset1:1
	ds_write2_b32 v29, v60, v61 offset1:1
	s_waitcnt lgkmcnt(0)
	ds_read2_b32 v[34:35], v14 offset0:33 offset1:41
	ds_read2_b32 v[36:37], v14 offset1:8
	ds_read2_b32 v[38:39], v14 offset0:66 offset1:74
	ds_read2_b32 v[40:41], v14 offset0:99 offset1:107
	ds_read2_b32 v[42:43], v14 offset0:132 offset1:140
	ds_read2_b32 v[44:45], v14 offset0:165 offset1:173
	ds_read2_b32 v[46:47], v14 offset0:198 offset1:206
	ds_read2_b32 v[48:49], v14 offset0:231 offset1:239
	ds_read2_b32 v[50:51], v14 offset0:49 offset1:57
	s_waitcnt lgkmcnt(7)
	v_cvt_pk_bf16_f32 v30, v36, v34
	s_waitcnt lgkmcnt(5)
	v_cvt_pk_bf16_f32 v31, v38, v40
	s_waitcnt lgkmcnt(3)
	v_cvt_pk_bf16_f32 v32, v42, v44
	s_waitcnt lgkmcnt(1)
	v_cvt_pk_bf16_f32 v33, v46, v48
	global_store_dwordx4 v[62:63], v[30:33], off
	v_cvt_pk_bf16_f32 v34, v37, v35
	v_cvt_pk_bf16_f32 v35, v39, v41
	v_cvt_pk_bf16_f32 v36, v43, v45
	v_cvt_pk_bf16_f32 v37, v47, v49
	ds_read2_b32 v[38:39], v14 offset0:16 offset1:24
	ds_read2_b32 v[40:41], v14 offset0:82 offset1:90
	ds_read2_b32 v[42:43], v14 offset0:115 offset1:123
	ds_read2_b32 v[44:45], v14 offset0:148 offset1:156
	ds_read2_b32 v[46:47], v14 offset0:181 offset1:189
	ds_read2_b32 v[48:49], v14 offset0:214 offset1:222
	ds_read2_b32 v[52:53], v14 offset0:247 offset1:255
	global_store_dwordx4 v[64:65], v[34:37], off
	s_waitcnt lgkmcnt(6)
	v_cvt_pk_bf16_f32 v30, v38, v50
	s_waitcnt lgkmcnt(4)
	v_cvt_pk_bf16_f32 v31, v40, v42
	v_add_u32_e32 v34, s10, v12
	v_ashrrev_i32_e32 v35, 31, v34
	v_lshlrev_b64 v[34:35], 13, v[34:35]
	s_waitcnt lgkmcnt(2)
	v_cvt_pk_bf16_f32 v32, v44, v46
	s_waitcnt lgkmcnt(0)
	v_cvt_pk_bf16_f32 v33, v48, v52
	v_lshl_add_u64 v[34:35], v[66:67], 0, v[34:35]
	global_store_dwordx4 v[34:35], v[30:33], off
	v_add_u32_e32 v34, s10, v13
	v_ashrrev_i32_e32 v35, 31, v34
	v_lshlrev_b64 v[34:35], 13, v[34:35]
	v_cvt_pk_bf16_f32 v30, v39, v51
	v_cvt_pk_bf16_f32 v31, v41, v43
	v_cvt_pk_bf16_f32 v32, v45, v47
	v_cvt_pk_bf16_f32 v33, v49, v53
	v_lshl_add_u64 v[34:35], v[66:67], 0, v[34:35]
	global_store_dwordx4 v[34:35], v[30:33], off
	s_waitcnt lgkmcnt(0)

.LBB0_317:
	s_andn2_b64 vcc, exec, s[10:11]
	s_cbranch_vccnz .LBB0_280
	s_ashr_i32 s10, s5, 31
	s_lshr_b32 s10, s10, 21
	s_add_i32 s17, s5, s10
	s_ashr_i32 s10, s17, 11
	s_ashr_i32 s11, s10, 31
	s_lshl_b64 s[12:13], s[10:11], 24
	s_add_u32 s22, s52, s12
	s_addc_u32 s13, s53, s13
	s_add_i32 s12, s10, -2
	s_cmpk_lt_i32 s5, 0x1000
	s_cselect_b32 s11, s11, 0
	s_cselect_b32 s10, s10, s12
	s_mov_b32 s12, 0x5400000
	s_cselect_b32 s12, s12, 0x2c00000
	s_lshl_b64 s[10:11], s[10:11], 23
	s_add_u32 s10, s94, s10
	s_addc_u32 s11, s95, s11
	s_add_u32 s23, s10, s12
	s_addc_u32 s24, s11, 0
	s_and_b32 s10, s17, 0xf800
	s_sub_i32 s5, s5, s10
	s_sext_i32_i16 s10, s5
	s_bfe_u32 s10, s10, 0x70018
	s_add_i32 s10, s5, s10
	s_sext_i32_i16 s11, s10
	s_and_b32 s10, s10, 0xff80
	s_sub_i32 s5, s5, s10
	s_sext_i32_i16 s5, s5
	s_ashr_i32 s11, s11, 7
	s_lshl_b32 s10, s5, 5
	s_lshl_b32 s12, s11, 6
	s_ashr_i32 s11, s10, 31
	s_lshl_b64 s[20:21], s[10:11], 2
	v_add_u32_e32 v30, s12, v10
	s_add_u32 s20, s22, s20
	s_addc_u32 s21, s13, s21
	v_ashrrev_i32_e32 v31, 31, v30
	v_lshl_add_u64 v[32:33], s[20:21], 0, v[152:153]
	v_lshlrev_b64 v[30:31], 14, v[30:31]
	v_lshl_add_u64 v[58:59], v[32:33], 0, v[30:31]
	v_add_co_u32_e32 v34, vcc, s76, v58
	s_mov_b32 s5, 0x40000
	s_nop 0
	v_addc_co_u32_e32 v35, vcc, 0, v59, vcc
	v_add_co_u32_e32 v38, vcc, s5, v58
	s_mov_b32 s5, 0x60000
	s_nop 0
	v_addc_co_u32_e32 v39, vcc, 0, v59, vcc
	v_add_co_u32_e32 v42, vcc, s5, v58
	s_mov_b32 s5, 0x80000
	s_nop 0
	v_addc_co_u32_e32 v43, vcc, 0, v59, vcc
	v_add_co_u32_e32 v46, vcc, s5, v58
	s_mov_b32 s5, 0xa0000
	s_nop 0
	v_addc_co_u32_e32 v47, vcc, 0, v59, vcc
	v_add_co_u32_e32 v50, vcc, s5, v58
	global_load_dwordx4 v[30:33], v[58:59], off nt
	s_nop 0
	global_load_dwordx4 v[34:37], v[34:35], off nt
	v_addc_co_u32_e32 v51, vcc, 0, v59, vcc
	global_load_dwordx4 v[38:41], v[38:39], off nt
	s_nop 0
	global_load_dwordx4 v[42:45], v[42:43], off nt
	s_nop 0
	global_load_dwordx4 v[46:49], v[46:47], off nt
	s_nop 0
	global_load_dwordx4 v[50:53], v[50:51], off nt
	s_mov_b32 s5, 0xc0000
	v_add_co_u32_e32 v54, vcc, s5, v58
	s_mov_b32 s5, 0xe0000
	s_nop 0
	v_addc_co_u32_e32 v55, vcc, 0, v59, vcc
	global_load_dwordx4 v[54:57], v[54:55], off nt
	v_add_co_u32_e32 v58, vcc, s5, v58
	s_ashr_i32 s13, s12, 31
	s_nop 0
	v_addc_co_u32_e32 v59, vcc, 0, v59, vcc
	global_load_dwordx4 v[58:61], v[58:59], off nt
	s_lshl_b64 s[12:13], s[12:13], 1
	v_add_u32_e32 v62, s10, v10
	s_add_u32 s12, s23, s12
	v_mov_b32_e32 v9, v153
	v_ashrrev_i32_e32 v63, 31, v62
	s_addc_u32 s13, s24, s13
	v_lshlrev_b64 v[62:63], 11, v[62:63]
	v_lshl_add_u64 v[64:65], s[12:13], 0, v[8:9]
	s_waitcnt vmcnt(7)
	ds_write2_b32 v15, v30, v31 offset1:1
	ds_write2_b32 v15, v32, v33 offset0:2 offset1:3
	s_waitcnt vmcnt(6)
	ds_write2_b32 v16, v34, v35 offset1:1
	ds_write2_b32 v17, v36, v37 offset1:1
	s_waitcnt vmcnt(5)
	ds_write2_b32 v18, v38, v39 offset1:1
	ds_write2_b32 v19, v40, v41 offset1:1
	s_waitcnt vmcnt(4)
	ds_write2_b32 v20, v42, v43 offset1:1
	ds_write2_b32 v21, v44, v45 offset1:1
	s_waitcnt vmcnt(3)
	ds_write2_b32 v22, v46, v47 offset1:1
	ds_write2_b32 v23, v48, v49 offset1:1
	s_waitcnt vmcnt(2)
	ds_write2_b32 v24, v50, v51 offset1:1
	ds_write2_b32 v25, v52, v53 offset1:1
	s_waitcnt vmcnt(1)
	ds_write2_b32 v26, v54, v55 offset1:1
	ds_write2_b32 v27, v56, v57 offset1:1
	s_waitcnt vmcnt(0)
	ds_write2_b32 v28, v58, v59 offset1:1
	ds_write2_b32 v29, v60, v61 offset1:1
	s_waitcnt lgkmcnt(0)
	ds_read2_b32 v[34:35], v14 offset0:33 offset1:41
	ds_read2_b32 v[36:37], v14 offset1:8
	ds_read2_b32 v[38:39], v14 offset0:66 offset1:74
	ds_read2_b32 v[40:41], v14 offset0:99 offset1:107
	ds_read2_b32 v[42:43], v14 offset0:132 offset1:140
	ds_read2_b32 v[44:45], v14 offset0:165 offset1:173
	ds_read2_b32 v[46:47], v14 offset0:198 offset1:206
	ds_read2_b32 v[48:49], v14 offset0:231 offset1:239
	v_lshl_add_u64 v[50:51], v[64:65], 0, v[62:63]
	s_waitcnt lgkmcnt(6)
	v_cvt_pk_bf16_f32 v30, v36, v34
	s_waitcnt lgkmcnt(4)
	v_cvt_pk_bf16_f32 v31, v38, v40
	s_waitcnt lgkmcnt(2)
	v_cvt_pk_bf16_f32 v32, v42, v44
	s_waitcnt lgkmcnt(0)
	v_cvt_pk_bf16_f32 v33, v46, v48
	global_store_dwordx4 v[50:51], v[30:33], off
	v_cvt_pk_bf16_f32 v34, v37, v35
	v_cvt_pk_bf16_f32 v35, v39, v41
	v_add_u32_e32 v30, s10, v11
	v_ashrrev_i32_e32 v31, 31, v30
	v_cvt_pk_bf16_f32 v36, v43, v45
	v_cvt_pk_bf16_f32 v37, v47, v49
	v_lshlrev_b64 v[30:31], 11, v[30:31]
	ds_read2_b32 v[38:39], v14 offset0:49 offset1:57
	ds_read2_b32 v[40:41], v14 offset0:16 offset1:24
	ds_read2_b32 v[42:43], v14 offset0:82 offset1:90
	ds_read2_b32 v[44:45], v14 offset0:115 offset1:123
	ds_read2_b32 v[46:47], v14 offset0:148 offset1:156
	ds_read2_b32 v[48:49], v14 offset0:181 offset1:189
	ds_read2_b32 v[50:51], v14 offset0:214 offset1:222
	ds_read2_b32 v[52:53], v14 offset0:247 offset1:255
	v_lshl_add_u64 v[30:31], v[64:65], 0, v[30:31]
	global_store_dwordx4 v[30:31], v[34:37], off
	s_waitcnt lgkmcnt(6)
	v_cvt_pk_bf16_f32 v30, v40, v38
	s_waitcnt lgkmcnt(4)
	v_cvt_pk_bf16_f32 v31, v42, v44
	v_add_u32_e32 v34, s10, v12
	v_ashrrev_i32_e32 v35, 31, v34
	v_lshlrev_b64 v[34:35], 11, v[34:35]
	s_waitcnt lgkmcnt(2)
	v_cvt_pk_bf16_f32 v32, v46, v48
	s_waitcnt lgkmcnt(0)
	v_cvt_pk_bf16_f32 v33, v50, v52
	v_lshl_add_u64 v[34:35], v[64:65], 0, v[34:35]
	global_store_dwordx4 v[34:35], v[30:33], off
	v_add_u32_e32 v34, s10, v13
	v_ashrrev_i32_e32 v35, 31, v34
	v_lshlrev_b64 v[34:35], 11, v[34:35]
	v_cvt_pk_bf16_f32 v30, v41, v39
	v_cvt_pk_bf16_f32 v31, v43, v45
	v_cvt_pk_bf16_f32 v32, v47, v49
	v_cvt_pk_bf16_f32 v33, v51, v53
	v_lshl_add_u64 v[34:35], v[64:65], 0, v[34:35]
	global_store_dwordx4 v[34:35], v[30:33], off
	s_waitcnt lgkmcnt(0)
	s_branch .LBB0_280
